# FFN-in GEMM: each block computes two vertically adjacent 128x128 tiles sharing the weight tile (48 KB staged per k-step instead of 64 KB)
# speedup vs baseline: 1.0514x; 1.0179x over previous
; DI int lat_tile(int i) { return (i >> 4) * 18 + 2 + (i & 15); }
; template <int KSEL> DI void run_phase(const Params& p, int ph, char* lds) {
;     ...
;     case 8: {
;       EpiFfnIn e{p.ACT};
;       const int nm = last ? 128 : 144;
;       const int nconv = last ? 0 : NCONV_W1;
;       for (int i = 0, tm, tn; xcd_tile(bid, G, i, nm, 44, tm, tn); ++i) gemm_tile(p.HY, DM, p.Wffi, DM, DM, (last ? lat_tile(tm) : tm) * 128, tn * 128, lds, e);
.LBB0_118:
	s_andn2_b64 vcc, exec, s[0:1]
	s_cbranch_vccnz .LBB0_227
	v_readlane_b32 s0, v250, 4
	v_readlane_b32 s1, v250, 5
	s_and_b64 s[0:1], s[0:1], exec
	s_movk_i32 s0, 0x40
	s_cselect_b32 s26, s0, 0x48
	v_cvt_f32_ubyte0_e32 v1, s26
	v_rcp_iflag_f32_e32 v1, v1
	s_lshr_b32 s36, s26, 3
	v_readlane_b32 s0, v251, 50
	s_mul_i32 s27, s36, 44
	v_mul_f32_e32 v1, 0x4f7ffffe, v1
	v_cvt_u32_f32_e32 v1, v1
	s_mul_i32 s36, s36, s0
	s_sub_i32 s0, 0, s26
	s_mov_b32 s37, 0
	v_readfirstlane_b32 s1, v1
	s_mul_i32 s0, s0, s1
	s_mul_hi_u32 s0, s1, s0
	s_add_i32 s38, s1, s0
	s_branch .LBB0_121

; #define LAS __attribute__((address_space(3)))
; DI int opaque_tid() { int t = threadIdx.x; asm volatile("" : "+v"(t)); return t; }
; DI int lat_tile(int i) { return (i >> 4) * 18 + 2 + (i & 15); }
; template <class Epi>
; DI void gemm_tile(const bf16_t* __restrict__ A, int lda, const bf16_t* __restrict__ Bt, int ldb, int K, int row0, int col0, char* lds, const Epi& epi) {
;   const int tid = opaque_tid(), lane = tid & 63, wid = tid >> 6, wr = wid >> 1, wc = wid & 1, fr = lane & 15, fq = lane >> 4;
;   const bf16_t* ag[4];
;   const bf16_t* bg[4];
; #pragma unroll
;   for (int i = 0; i < 4; ++i) {
;     const int id = i * 256 + tid, r = id >> 3, cp = id & 7, c = cp ^ ((r >> 1) & 7);
;     ag[i] = A + (size_t)(row0 + r) * lda + c * 8;
;     bg[i] = Bt + (size_t)(col0 + r) * ldb + c * 8;
;   }
;   f32x4 acc[4][4];
; #pragma unroll
;   for (int m = 0; m < 4; ++m)
; #pragma unroll
;     for (int n = 0; n < 4; ++n) acc[m][n] = (f32x4){0.f, 0.f, 0.f, 0.f};
;   const int KT = K >> 6;
;   auto stage_a = [&](int kt, int buf) {
;     char* sa = lds + buf * 32768;
; #pragma unroll
;     for (int i = 0; i < 4; ++i)
;       __builtin_amdgcn_global_load_lds((const void __attribute__((address_space(1)))*)(ag[i] + kt * 64), (void LAS*)(sa + (i * 256 + tid) * 16), 16, 0, 0);
;   };
;   auto stage_b = [&](int kt, int buf) {
;     char* sb = lds + buf * 32768 + 16384;
; #pragma unroll
;     for (int i = 0; i < 4; ++i)
;       __builtin_amdgcn_global_load_lds((const void __attribute__((address_space(1)))*)(bg[i] + kt * 64), (void LAS*)(sb + (i * 256 + tid) * 16), 16, 0, 0);
;   };
;   __syncthreads();
;   stage_a(0, 0); stage_b(0, 0);
; template <int KSEL> DI void run_phase(const Params& p, int ph, char* lds) {
;     ...
;       for (int i = 0, tm, tn; xcd_tile(bid, G, i, nm, 44, tm, tn); ++i) gemm_tile(p.HY, DM, p.Wffi, DM, DM, (last ? lat_tile(tm) : tm) * 128, tn * 128, lds, e);
.LBB0_132:
	s_mov_b64 s[2:3], -1
	s_and_b64 vcc, exec, s[0:1]
	s_cbranch_vccz .LBB0_120
	s_lshl_b32 s28, s28, 1
	v_readlane_b32 s0, v250, 4
	v_readlane_b32 s1, v250, 5
	s_andn2_b64 vcc, exec, s[0:1]
	s_cbranch_vccnz .LBB0_135
	s_ashr_i32 s0, s28, 4
	s_mul_i32 s0, s0, 18
	s_and_b32 s1, s28, 15
	s_add_i32 s0, s1, s0
	s_add_i32 s28, s0, 2
.LBB0_135:
	v_mov_b32_e32 v34, v138
	s_lshl_b32 s2, s28, 7
	v_lshrrev_b32_e32 v35, 4, v34
	v_xor_b32_e32 v1, v35, v34
	v_lshlrev_b32_e32 v1, 4, v1
	s_lshl_b32 s3, s29, 7
	v_and_b32_e32 v110, 0x70, v1
	v_ashrrev_i32_e32 v1, 3, v34
	v_add_u32_e32 v6, s2, v1
	v_add_u32_e32 v10, s3, v1
	v_add_u32_e32 v1, 0x100, v34
	v_readlane_b32 s4, v253, 36
	v_ashrrev_i32_e32 v1, 3, v1
	v_readlane_b32 s8, v253, 40
	v_readlane_b32 s9, v253, 41
	v_ashrrev_i32_e32 v7, 31, v6
	v_add_u32_e32 v14, s2, v1
	v_add_u32_e32 v18, s3, v1
	v_add_u32_e32 v1, 0x200, v34
	s_waitcnt vmcnt(6)
	v_lshlrev_b32_e32 v92, 4, v34
	v_lshl_add_u64 v[2:3], s[8:9], 0, v[110:111]
	v_lshlrev_b64 v[6:7], 11, v[6:7]
	v_ashrrev_i32_e32 v1, 3, v1
	v_readfirstlane_b32 s0, v92
	v_lshl_add_u64 v[8:9], v[2:3], 0, v[6:7]
	v_add_u32_e32 v22, s2, v1
	v_add_u32_e32 v26, s3, v1
	v_add_u32_e32 v1, 0x300, v34
	s_mov_b32 m0, s0
	v_ashrrev_i32_e32 v15, 31, v14
	v_ashrrev_i32_e32 v1, 3, v1
	s_barrier
	global_load_lds_dwordx4 v[8:9], off
	v_add_u32_e32 v8, 0x1000, v92
	v_lshlrev_b64 v[14:15], 11, v[14:15]
	v_ashrrev_i32_e32 v23, 31, v22
	v_add_u32_e32 v30, s2, v1
	v_readfirstlane_b32 s0, v8
	v_add_u32_e32 v8, 0x2000, v92
	v_lshl_add_u64 v[16:17], v[2:3], 0, v[14:15]
	v_lshlrev_b64 v[22:23], 11, v[22:23]
	v_ashrrev_i32_e32 v31, 31, v30
	s_mov_b32 m0, s0
	v_readfirstlane_b32 s0, v8
	v_add_u32_e32 v8, 0x3000, v92
	v_lshl_add_u64 v[24:25], v[2:3], 0, v[22:23]
	v_lshlrev_b64 v[30:31], 11, v[30:31]
	global_load_lds_dwordx4 v[16:17], off
	s_mov_b32 m0, s0
	v_readfirstlane_b32 s0, v8
	v_lshl_add_u64 v[2:3], v[2:3], 0, v[30:31]
	global_load_lds_dwordx4 v[24:25], off
	s_mov_b32 m0, s0
	v_readlane_b32 s5, v253, 37
	v_ashrrev_i32_e32 v11, 31, v10
	global_load_lds_dwordx4 v[2:3], off
	v_add_u32_e32 v2, 0x4000, v92
	v_lshl_add_u64 v[4:5], s[4:5], 0, v[110:111]
	v_lshlrev_b64 v[10:11], 11, v[10:11]
	v_ashrrev_i32_e32 v19, 31, v18
	v_readfirstlane_b32 s0, v2
	v_add_u32_e32 v2, 0x5000, v92
	v_lshl_add_u64 v[12:13], v[4:5], 0, v[10:11]
	v_lshlrev_b64 v[18:19], 11, v[18:19]
	v_ashrrev_i32_e32 v27, 31, v26
	v_add_u32_e32 v32, s3, v1
	s_mov_b32 m0, s0
	v_readfirstlane_b32 s0, v2
	v_add_u32_e32 v2, 0x6000, v92
	v_lshl_add_u64 v[20:21], v[4:5], 0, v[18:19]
	v_lshlrev_b64 v[26:27], 11, v[26:27]
	v_ashrrev_i32_e32 v33, 31, v32
	global_load_lds_dwordx4 v[12:13], off
	s_mov_b32 m0, s0
	v_readfirstlane_b32 s0, v2
	v_add_u32_e32 v2, 0x7000, v92
	v_lshl_add_u64 v[28:29], v[4:5], 0, v[26:27]
	v_lshlrev_b64 v[32:33], 11, v[32:33]
	global_load_lds_dwordx4 v[20:21], off
	s_mov_b32 m0, s0
	v_readfirstlane_b32 s0, v2
	v_lshl_add_u64 v[4:5], v[4:5], 0, v[32:33]
	global_load_lds_dwordx4 v[28:29], off
	s_mov_b32 m0, s0
	v_and_b32_e32 v87, 15, v34
	global_load_lds_dwordx4 v[4:5], off
	v_bfe_u32 v86, v34, 6, 1
	v_ashrrev_i32_e32 v88, 7, v34
	v_bfe_u32 v1, v34, 4, 2
	v_bfe_u32 v2, v34, 1, 3
	v_lshlrev_b32_e32 v3, 7, v87
	v_lshl_or_b32 v89, v88, 13, v3
	v_lshl_or_b32 v91, v86, 13, v3
	v_bitop3_b32 v3, v1, v2, 4 bitop3:0x36
	v_bitop3_b32 v2, v35, v2, 3 bitop3:0x6c
	v_lshlrev_b32_e32 v93, 4, v2
	v_bitop3_b32 v2, v35, 7, v34 bitop3:0x48
	v_lshlrev_b32_e32 v2, 4, v2
	v_readlane_b32 s0, v253, 13
	v_or_b32_e32 v10, v10, v2
	v_readlane_b32 s1, v253, 14
	v_or_b32_e32 v18, v18, v2
	v_or_b32_e32 v26, v26, v2
	v_or_b32_e32 v32, v32, v2
	s_waitcnt vmcnt(0)
	v_lshl_add_u64 v[66:67], s[0:1], 0, v[10:11]
	v_lshl_add_u64 v[68:69], s[0:1], 0, v[18:19]
	v_lshl_add_u64 v[70:71], s[0:1], 0, v[26:27]
	v_lshl_add_u64 v[72:73], s[0:1], 0, v[32:33]
	v_readlane_b32 s0, v254, 60
	v_or_b32_e32 v6, v6, v2
	v_readlane_b32 s1, v254, 61
	v_or_b32_e32 v14, v14, v2
	v_or_b32_e32 v22, v22, v2
	v_or_b32_e32 v30, v30, v2
	v_mov_b32_e32 v2, 0
	v_lshlrev_b32_e32 v90, 4, v3
	v_lshl_add_u64 v[74:75], s[0:1], 0, v[6:7]
	v_lshl_add_u64 v[76:77], s[0:1], 0, v[14:15]
	v_lshl_add_u64 v[78:79], s[0:1], 0, v[22:23]
	v_lshl_add_u64 v[80:81], s[0:1], 0, v[30:31]
	s_mov_b64 s[0:1], 0
	s_mov_b32 s28, 0x8000
	v_mov_b32_e32 v3, v2
	v_mov_b32_e32 v4, v2
	v_mov_b32_e32 v5, v2
	v_mov_b32_e32 v6, v2
	v_mov_b32_e32 v7, v2
	v_mov_b32_e32 v8, v2
	v_mov_b32_e32 v9, v2
	v_mov_b32_e32 v10, v2
	v_mov_b32_e32 v11, v2
	v_mov_b32_e32 v12, v2
	v_mov_b32_e32 v13, v2
	v_mov_b32_e32 v14, v2
	v_mov_b32_e32 v15, v2
	v_mov_b32_e32 v16, v2
	v_mov_b32_e32 v17, v2
	v_mov_b32_e32 v18, v2
	v_mov_b32_e32 v19, v2
	v_mov_b32_e32 v20, v2
	v_mov_b32_e32 v21, v2
	v_mov_b32_e32 v22, v2
	v_mov_b32_e32 v23, v2
	v_mov_b32_e32 v24, v2
	v_mov_b32_e32 v25, v2
	v_mov_b32_e32 v26, v2
	v_mov_b32_e32 v27, v2
	v_mov_b32_e32 v28, v2
	v_mov_b32_e32 v29, v2
	v_mov_b32_e32 v30, v2
	v_mov_b32_e32 v31, v2
	v_mov_b32_e32 v32, v2
	v_mov_b32_e32 v33, v2
	v_mov_b32_e32 v34, v2
	v_mov_b32_e32 v35, v2
	v_mov_b32_e32 v36, v2
	v_mov_b32_e32 v37, v2
	v_mov_b32_e32 v38, v2
	v_mov_b32_e32 v39, v2
	v_mov_b32_e32 v40, v2
	v_mov_b32_e32 v41, v2
	v_mov_b32_e32 v42, v2
	v_mov_b32_e32 v43, v2
	v_mov_b32_e32 v44, v2
	v_mov_b32_e32 v45, v2
	v_mov_b32_e32 v46, v2
	v_mov_b32_e32 v47, v2
	v_mov_b32_e32 v48, v2
	v_mov_b32_e32 v49, v2
	v_mov_b32_e32 v50, v2
	v_mov_b32_e32 v51, v2
	v_mov_b32_e32 v52, v2
	v_mov_b32_e32 v53, v2
	v_mov_b32_e32 v54, v2
	v_mov_b32_e32 v55, v2
	v_mov_b32_e32 v56, v2
	v_mov_b32_e32 v57, v2
	v_mov_b32_e32 v58, v2
	v_mov_b32_e32 v59, v2
	v_mov_b32_e32 v60, v2
	v_mov_b32_e32 v61, v2
	v_mov_b32_e32 v62, v2
; #define LAS __attribute__((address_space(3)))
; template <class Epi>
; DI void gemm_tile(const bf16_t* __restrict__ A, int lda, const bf16_t* __restrict__ Bt, int ldb, int K, int row0, int col0, char* lds, const Epi& epi) {
;     ...
;   f32x4 acc[4][4];
; #pragma unroll
;   for (int m = 0; m < 4; ++m)
; #pragma unroll
;     for (int n = 0; n < 4; ++n) acc[m][n] = (f32x4){0.f, 0.f, 0.f, 0.f};
;   const int KT = K >> 6;
;   auto stage_a = [&](int kt, int buf) {
;     char* sa = lds + buf * 32768;
; #pragma unroll
;     for (int i = 0; i < 4; ++i)
;       __builtin_amdgcn_global_load_lds((const void __attribute__((address_space(1)))*)(ag[i] + kt * 64), (void LAS*)(sa + (i * 256 + tid) * 16), 16, 0, 0);
;   };
;   auto stage_b = [&](int kt, int buf) {
;     char* sb = lds + buf * 32768 + 16384;
; #pragma unroll
;     for (int i = 0; i < 4; ++i)
;       __builtin_amdgcn_global_load_lds((const void __attribute__((address_space(1)))*)(bg[i] + kt * 64), (void LAS*)(sb + (i * 256 + tid) * 16), 16, 0, 0);
;   };
;   __syncthreads();
;   stage_a(0, 0); stage_b(0, 0);
;   const int swz = fr >> 1;
;   for (int kt = 0; kt < KT; ++kt) {
;     asm volatile("s_waitcnt vmcnt(0)" ::: "memory");
;     __syncthreads();
;     const char* sa = lds + (kt & 1) * 32768 + (wr * 64 + fr) * 128;
;     const char* sb = lds + (kt & 1) * 32768 + 16384 + (wc * 64 + fr) * 128;
; #pragma unroll
;     for (int kk = 0; kk < 2; ++kk) {
;       if (kt + 1 < KT) { if (kk == 0) stage_a(kt + 1, (kt + 1) & 1); else stage_b(kt + 1, (kt + 1) & 1); }
;       bf16x8 a[4], b[4];
;       const int co = ((kk * 4 + fq) ^ swz) * 16;
; #pragma unroll
;       for (int m = 0; m < 4; ++m) a[m] = *(const bf16x8*)(sa + m * 2048 + co);
; #pragma unroll
;       for (int n = 0; n < 4; ++n) b[n] = *(const bf16x8*)(sb + n * 2048 + co);
; #pragma unroll
;       for (int m = 0; m < 4; ++m)
; #pragma unroll
;         for (int n = 0; n < 4; ++n) acc[m][n] = __builtin_amdgcn_mfma_f32_16x16x32_bf16(b[n], a[m], acc[m][n], 0, 0, 0);
;     }
	v_mov_b32_e32 v63, v2
	v_mov_b32_e32 v64, v2
	v_mov_b32_e32 v65, v2
	v_readlane_b32 s6, v253, 38
	v_readlane_b32 s7, v253, 39
	v_readlane_b32 s10, v253, 42
	v_readlane_b32 s11, v253, 43
	v_readlane_b32 s12, v253, 44
	v_readlane_b32 s13, v253, 45
	v_readlane_b32 s14, v253, 46
	v_readlane_b32 s15, v253, 47
	v_readlane_b32 s16, v253, 48
	v_readlane_b32 s17, v253, 49
	v_readlane_b32 s18, v253, 50
	v_readlane_b32 s19, v253, 51
	v_mov_b32_e32 v162, 0
	v_mov_b32_e32 v163, 0
	v_mov_b32_e32 v164, 0
	v_mov_b32_e32 v165, 0
	v_mov_b32_e32 v166, 0
	v_mov_b32_e32 v167, 0
	v_mov_b32_e32 v168, 0
	v_mov_b32_e32 v169, 0
	v_mov_b32_e32 v170, 0
	v_mov_b32_e32 v171, 0
	v_mov_b32_e32 v172, 0
	v_mov_b32_e32 v173, 0
	v_mov_b32_e32 v174, 0
	v_mov_b32_e32 v175, 0
	v_mov_b32_e32 v176, 0
	v_mov_b32_e32 v177, 0
	v_mov_b32_e32 v178, 0
	v_mov_b32_e32 v179, 0
	v_mov_b32_e32 v180, 0
	v_mov_b32_e32 v181, 0
	v_mov_b32_e32 v182, 0
	v_mov_b32_e32 v183, 0
	v_mov_b32_e32 v184, 0
	v_mov_b32_e32 v185, 0
	v_mov_b32_e32 v186, 0
	v_mov_b32_e32 v187, 0
	v_mov_b32_e32 v188, 0
	v_mov_b32_e32 v189, 0
	v_mov_b32_e32 v190, 0
	v_mov_b32_e32 v191, 0
	v_mov_b32_e32 v192, 0
	v_mov_b32_e32 v193, 0
	v_mov_b32_e32 v194, 0
	v_mov_b32_e32 v195, 0
	v_mov_b32_e32 v196, 0
	v_mov_b32_e32 v197, 0
	v_mov_b32_e32 v198, 0
	v_mov_b32_e32 v199, 0
	v_mov_b32_e32 v200, 0
	v_mov_b32_e32 v201, 0
	v_mov_b32_e32 v202, 0
	v_mov_b32_e32 v203, 0
	v_mov_b32_e32 v204, 0
	v_mov_b32_e32 v205, 0
	v_mov_b32_e32 v206, 0
	v_mov_b32_e32 v207, 0
	v_mov_b32_e32 v208, 0
	v_mov_b32_e32 v209, 0
	v_mov_b32_e32 v210, 0
	v_mov_b32_e32 v211, 0
	v_mov_b32_e32 v212, 0
	v_mov_b32_e32 v213, 0
	v_mov_b32_e32 v214, 0
	v_mov_b32_e32 v215, 0
	v_mov_b32_e32 v216, 0
	v_mov_b32_e32 v217, 0
	v_mov_b32_e32 v218, 0
	v_mov_b32_e32 v219, 0
	v_mov_b32_e32 v220, 0
	v_mov_b32_e32 v221, 0
	v_mov_b32_e32 v222, 0
	v_mov_b32_e32 v223, 0
	v_mov_b32_e32 v224, 0
	v_mov_b32_e32 v225, 0
	v_readfirstlane_b32 s21, v92
	v_add_u32_e32 v242, v89, v93
	v_add_u32_e32 v243, v91, v93
	v_add_u32_e32 v244, v89, v90
	v_add_u32_e32 v245, v91, v90
	s_mov_b32 s0, 0x3ff80
	s_mov_b32 s1, 0
	s_add_i32 m0, s21, 0x8000
	v_lshl_add_u64 v[82:83], v[74:75], 0, s[0:1]
	global_load_lds_dwordx4 v[82:83], off
	s_add_i32 m0, m0, 0x1000
	v_lshl_add_u64 v[82:83], v[76:77], 0, s[0:1]
	global_load_lds_dwordx4 v[82:83], off
	s_add_i32 m0, m0, 0x1000
	v_lshl_add_u64 v[82:83], v[78:79], 0, s[0:1]
	global_load_lds_dwordx4 v[82:83], off
	s_add_i32 m0, m0, 0x1000
	v_lshl_add_u64 v[82:83], v[80:81], 0, s[0:1]
	global_load_lds_dwordx4 v[82:83], off
	s_mov_b64 s[0:1], 0
.LBB0_136:
	s_waitcnt vmcnt(0)
	s_barrier
	ds_read_b128 v[94:97], v242
	ds_read_b128 v[98:101], v242 offset:2048
	ds_read_b128 v[102:105], v242 offset:4096
	ds_read_b128 v[106:109], v242 offset:6144
	ds_read_b128 v[116:119], v243 offset:16384
	ds_read_b128 v[120:123], v243 offset:18432
	ds_read_b128 v[124:127], v243 offset:20480
	ds_read_b128 v[128:131], v243 offset:22528
	ds_read_b128 v[226:229], v242 offset:32768
	ds_read_b128 v[230:233], v242 offset:34816
	ds_read_b128 v[234:237], v242 offset:36864
	ds_read_b128 v[238:241], v242 offset:38912
	s_waitcnt lgkmcnt(0)
	v_mfma_f32_16x16x32_bf16 v[62:65], v[116:119], v[94:97], v[62:65]
	v_mfma_f32_16x16x32_bf16 v[58:61], v[120:123], v[94:97], v[58:61]
	v_mfma_f32_16x16x32_bf16 v[54:57], v[124:127], v[94:97], v[54:57]
	v_mfma_f32_16x16x32_bf16 v[50:53], v[128:131], v[94:97], v[50:53]
	v_mfma_f32_16x16x32_bf16 v[46:49], v[116:119], v[98:101], v[46:49]
	v_mfma_f32_16x16x32_bf16 v[42:45], v[120:123], v[98:101], v[42:45]
	v_mfma_f32_16x16x32_bf16 v[38:41], v[124:127], v[98:101], v[38:41]
	v_mfma_f32_16x16x32_bf16 v[34:37], v[128:131], v[98:101], v[34:37]
	v_mfma_f32_16x16x32_bf16 v[30:33], v[116:119], v[102:105], v[30:33]
	v_mfma_f32_16x16x32_bf16 v[26:29], v[120:123], v[102:105], v[26:29]
	v_mfma_f32_16x16x32_bf16 v[22:25], v[124:127], v[102:105], v[22:25]
	v_mfma_f32_16x16x32_bf16 v[18:21], v[128:131], v[102:105], v[18:21]
	v_mfma_f32_16x16x32_bf16 v[14:17], v[116:119], v[106:109], v[14:17]
	v_mfma_f32_16x16x32_bf16 v[10:13], v[120:123], v[106:109], v[10:13]
	v_mfma_f32_16x16x32_bf16 v[6:9], v[124:127], v[106:109], v[6:9]
	v_mfma_f32_16x16x32_bf16 v[2:5], v[128:131], v[106:109], v[2:5]
	v_mfma_f32_16x16x32_bf16 v[222:225], v[116:119], v[226:229], v[222:225]
	v_mfma_f32_16x16x32_bf16 v[218:221], v[120:123], v[226:229], v[218:221]
	v_mfma_f32_16x16x32_bf16 v[214:217], v[124:127], v[226:229], v[214:217]
	v_mfma_f32_16x16x32_bf16 v[210:213], v[128:131], v[226:229], v[210:213]
	v_mfma_f32_16x16x32_bf16 v[206:209], v[116:119], v[230:233], v[206:209]
	v_mfma_f32_16x16x32_bf16 v[202:205], v[120:123], v[230:233], v[202:205]
	v_mfma_f32_16x16x32_bf16 v[198:201], v[124:127], v[230:233], v[198:201]
	v_mfma_f32_16x16x32_bf16 v[194:197], v[128:131], v[230:233], v[194:197]
	v_mfma_f32_16x16x32_bf16 v[190:193], v[116:119], v[234:237], v[190:193]
	v_mfma_f32_16x16x32_bf16 v[186:189], v[120:123], v[234:237], v[186:189]
	v_mfma_f32_16x16x32_bf16 v[182:185], v[124:127], v[234:237], v[182:185]
	v_mfma_f32_16x16x32_bf16 v[178:181], v[128:131], v[234:237], v[178:181]
	v_mfma_f32_16x16x32_bf16 v[174:177], v[116:119], v[238:241], v[174:177]
	v_mfma_f32_16x16x32_bf16 v[170:173], v[120:123], v[238:241], v[170:173]
	v_mfma_f32_16x16x32_bf16 v[166:169], v[124:127], v[238:241], v[166:169]
	v_mfma_f32_16x16x32_bf16 v[162:165], v[128:131], v[238:241], v[162:165]
	ds_read_b128 v[94:97], v244
	ds_read_b128 v[98:101], v244 offset:2048
	ds_read_b128 v[102:105], v244 offset:4096
	ds_read_b128 v[106:109], v244 offset:6144
	ds_read_b128 v[116:119], v245 offset:16384
	ds_read_b128 v[120:123], v245 offset:18432
	ds_read_b128 v[124:127], v245 offset:20480
	ds_read_b128 v[128:131], v245 offset:22528
	ds_read_b128 v[226:229], v244 offset:32768
	ds_read_b128 v[230:233], v244 offset:34816
	ds_read_b128 v[234:237], v244 offset:36864
	ds_read_b128 v[238:241], v244 offset:38912
	s_waitcnt lgkmcnt(0)
	s_barrier
; DI unsigned pk_bf16(float lo, float hi) { f32x2 v = {lo, hi}; bf16v2 b = __builtin_convertvector(v, bf16v2); return __builtin_bit_cast(unsigned, b); }
; template <class Epi>
; DI void gemm_tile(const bf16_t* __restrict__ A, int lda, const bf16_t* __restrict__ Bt, int ldb, int K, int row0, int col0, char* lds, const Epi& epi) {
;     ...
;     for (int kk = 0; kk < 2; ++kk) {
;       if (kt + 1 < KT) { if (kk == 0) stage_a(kt + 1, (kt + 1) & 1); else stage_b(kt + 1, (kt + 1) & 1); }
;       bf16x8 a[4], b[4];
;       const int co = ((kk * 4 + fq) ^ swz) * 16;
; #pragma unroll
;       for (int m = 0; m < 4; ++m) a[m] = *(const bf16x8*)(sa + m * 2048 + co);
; #pragma unroll
;       for (int n = 0; n < 4; ++n) b[n] = *(const bf16x8*)(sb + n * 2048 + co);
; #pragma unroll
;       for (int m = 0; m < 4; ++m)
; #pragma unroll
;         for (int n = 0; n < 4; ++n) acc[m][n] = __builtin_amdgcn_mfma_f32_16x16x32_bf16(b[n], a[m], acc[m][n], 0, 0, 0);
;   DI void operator()(const f32x4 (&acc)[4][4], int r0, int c0, int fr, int fq) const {
;     const int cb = (c0 >> 6) * 32;
; #pragma unroll
;     for (int m = 0; m < 4; ++m)
; #pragma unroll
;       for (int n = 0; n < 2; ++n) {
;         float o[4];
; #pragma unroll
;         for (int j = 0; j < 4; ++j) { float g = acc[m][n][j]; o[j] = g * __builtin_amdgcn_rcpf(1.f + __expf(-g)) * acc[m][n + 2][j]; }
;         u32x2 w = {pk_bf16(o[0], o[1]), pk_bf16(o[2], o[3])};
;         *(u32x2*)(ACT + (size_t)(r0 + m * 16 + fr) * 2816 + cb + n * 16 + fq * 4) = w;
;       }
	s_cmpk_eq_i32 s0, 0x780
	s_cbranch_scc1 .Lffi2_noissue
	s_mov_b32 m0, s21
	v_lshl_add_u64 v[82:83], v[74:75], 0, s[0:1]
	global_load_lds_dwordx4 v[82:83], off
	s_add_i32 m0, m0, 0x1000
	v_lshl_add_u64 v[84:85], v[76:77], 0, s[0:1]
	global_load_lds_dwordx4 v[84:85], off
	s_add_i32 m0, m0, 0x1000
	v_lshl_add_u64 v[82:83], v[78:79], 0, s[0:1]
	global_load_lds_dwordx4 v[82:83], off
	s_add_i32 m0, m0, 0x1000
	v_lshl_add_u64 v[84:85], v[80:81], 0, s[0:1]
	global_load_lds_dwordx4 v[84:85], off
	s_add_i32 m0, m0, 0x1000
	v_lshl_add_u64 v[82:83], v[66:67], 0, s[0:1]
	global_load_lds_dwordx4 v[82:83], off
	s_add_i32 m0, m0, 0x1000
	v_lshl_add_u64 v[84:85], v[68:69], 0, s[0:1]
	global_load_lds_dwordx4 v[84:85], off
	s_add_i32 m0, m0, 0x1000
	v_lshl_add_u64 v[82:83], v[70:71], 0, s[0:1]
	global_load_lds_dwordx4 v[82:83], off
	s_add_i32 m0, m0, 0x1000
	v_lshl_add_u64 v[84:85], v[72:73], 0, s[0:1]
	global_load_lds_dwordx4 v[84:85], off
	s_add_i32 m0, m0, 0x1000
	s_add_u32 s20, s0, 0x40000
	v_add_co_u32_e32 v82, vcc, s20, v74
	v_addc_co_u32_e32 v83, vcc, 0, v75, vcc
	global_load_lds_dwordx4 v[82:83], off
	s_add_i32 m0, m0, 0x1000
	v_add_co_u32_e32 v84, vcc, s20, v76
	v_addc_co_u32_e32 v85, vcc, 0, v77, vcc
	global_load_lds_dwordx4 v[84:85], off
	s_add_i32 m0, m0, 0x1000
	v_add_co_u32_e32 v82, vcc, s20, v78
	v_addc_co_u32_e32 v83, vcc, 0, v79, vcc
	global_load_lds_dwordx4 v[82:83], off
	s_add_i32 m0, m0, 0x1000
	v_add_co_u32_e32 v84, vcc, s20, v80
	v_addc_co_u32_e32 v85, vcc, 0, v81, vcc
	global_load_lds_dwordx4 v[84:85], off
.Lffi2_noissue:
	v_mfma_f32_16x16x32_bf16 v[62:65], v[116:119], v[94:97], v[62:65]
	v_mfma_f32_16x16x32_bf16 v[58:61], v[120:123], v[94:97], v[58:61]
	v_mfma_f32_16x16x32_bf16 v[54:57], v[124:127], v[94:97], v[54:57]
	v_mfma_f32_16x16x32_bf16 v[50:53], v[128:131], v[94:97], v[50:53]
	v_mfma_f32_16x16x32_bf16 v[46:49], v[116:119], v[98:101], v[46:49]
	v_mfma_f32_16x16x32_bf16 v[42:45], v[120:123], v[98:101], v[42:45]
	v_mfma_f32_16x16x32_bf16 v[38:41], v[124:127], v[98:101], v[38:41]
	v_mfma_f32_16x16x32_bf16 v[34:37], v[128:131], v[98:101], v[34:37]
	v_mfma_f32_16x16x32_bf16 v[30:33], v[116:119], v[102:105], v[30:33]
	v_mfma_f32_16x16x32_bf16 v[26:29], v[120:123], v[102:105], v[26:29]
	v_mfma_f32_16x16x32_bf16 v[22:25], v[124:127], v[102:105], v[22:25]
	v_mfma_f32_16x16x32_bf16 v[18:21], v[128:131], v[102:105], v[18:21]
	v_mfma_f32_16x16x32_bf16 v[14:17], v[116:119], v[106:109], v[14:17]
	v_mfma_f32_16x16x32_bf16 v[10:13], v[120:123], v[106:109], v[10:13]
	v_mfma_f32_16x16x32_bf16 v[6:9], v[124:127], v[106:109], v[6:9]
	v_mfma_f32_16x16x32_bf16 v[2:5], v[128:131], v[106:109], v[2:5]
	v_mfma_f32_16x16x32_bf16 v[222:225], v[116:119], v[226:229], v[222:225]
	v_mfma_f32_16x16x32_bf16 v[218:221], v[120:123], v[226:229], v[218:221]
	v_mfma_f32_16x16x32_bf16 v[214:217], v[124:127], v[226:229], v[214:217]
	v_mfma_f32_16x16x32_bf16 v[210:213], v[128:131], v[226:229], v[210:213]
	v_mfma_f32_16x16x32_bf16 v[206:209], v[116:119], v[230:233], v[206:209]
	v_mfma_f32_16x16x32_bf16 v[202:205], v[120:123], v[230:233], v[202:205]
	v_mfma_f32_16x16x32_bf16 v[198:201], v[124:127], v[230:233], v[198:201]
	v_mfma_f32_16x16x32_bf16 v[194:197], v[128:131], v[230:233], v[194:197]
	v_mfma_f32_16x16x32_bf16 v[190:193], v[116:119], v[234:237], v[190:193]
	v_mfma_f32_16x16x32_bf16 v[186:189], v[120:123], v[234:237], v[186:189]
	v_mfma_f32_16x16x32_bf16 v[182:185], v[124:127], v[234:237], v[182:185]
	v_mfma_f32_16x16x32_bf16 v[178:181], v[128:131], v[234:237], v[178:181]
	v_mfma_f32_16x16x32_bf16 v[174:177], v[116:119], v[238:241], v[174:177]
	v_mfma_f32_16x16x32_bf16 v[170:173], v[120:123], v[238:241], v[170:173]
	v_mfma_f32_16x16x32_bf16 v[166:169], v[124:127], v[238:241], v[166:169]
	v_mfma_f32_16x16x32_bf16 v[162:165], v[128:131], v[238:241], v[162:165]
	s_add_u32 s0, s0, 0x80
	s_cmpk_lg_i32 s0, 0x800
	s_cbranch_scc1 .LBB0_136
	s_add_i32 s37, s37, 1
	v_readlane_b32 s6, v253, 32
	v_readlane_b32 s7, v253, 33
	s_movk_i32 s20, 0x1600
	v_lshl_or_b32 v84, v86, 6, s3
	v_lshl_add_u32 v84, v1, 3, v84
	v_or_b32_e32 v85, s2, v87
	v_lshl_add_u32 v85, v88, 6, v85
	v_mad_u32_u24 v83, v85, s20, v84
	v_mul_f32_e32 v94, 0xbfb8aa3b, v62
	v_mul_f32_e32 v95, 0xbfb8aa3b, v63
	v_mul_f32_e32 v96, 0xbfb8aa3b, v64
	v_mul_f32_e32 v97, 0xbfb8aa3b, v65
	v_exp_f32_e32 v94, v94
	v_exp_f32_e32 v95, v95
	v_exp_f32_e32 v96, v96
	v_exp_f32_e32 v97, v97
	s_nop 0
	v_add_f32_e32 v94, 1.0, v94
	v_add_f32_e32 v95, 1.0, v95
	v_add_f32_e32 v96, 1.0, v96
	v_add_f32_e32 v97, 1.0, v97
	v_rcp_f32_e32 v94, v94
	v_rcp_f32_e32 v95, v95
	v_rcp_f32_e32 v96, v96
	v_rcp_f32_e32 v97, v97
	s_nop 0
	v_pk_mul_f32 v[94:95], v[62:63], v[94:95]
	v_pk_mul_f32 v[96:97], v[64:65], v[96:97]
	v_pk_mul_f32 v[94:95], v[54:55], v[94:95]
	v_pk_mul_f32 v[96:97], v[56:57], v[96:97]
	v_cvt_pk_bf16_f32 v98, v94, v95
	v_cvt_pk_bf16_f32 v99, v96, v97
	global_store_dwordx2 v83, v[98:99], s[6:7]
	v_mul_f32_e32 v94, 0xbfb8aa3b, v58
	v_mul_f32_e32 v95, 0xbfb8aa3b, v59
	v_mul_f32_e32 v96, 0xbfb8aa3b, v60
	v_mul_f32_e32 v97, 0xbfb8aa3b, v61
	v_exp_f32_e32 v94, v94
	v_exp_f32_e32 v95, v95
	v_exp_f32_e32 v96, v96
	v_exp_f32_e32 v97, v97
	s_nop 0
	v_add_f32_e32 v94, 1.0, v94
	v_add_f32_e32 v95, 1.0, v95
	v_add_f32_e32 v96, 1.0, v96
	v_add_f32_e32 v97, 1.0, v97
	v_rcp_f32_e32 v94, v94
	v_rcp_f32_e32 v95, v95
	v_rcp_f32_e32 v96, v96
	v_rcp_f32_e32 v97, v97
	s_nop 0
	v_pk_mul_f32 v[94:95], v[58:59], v[94:95]
	v_pk_mul_f32 v[96:97], v[60:61], v[96:97]
	v_pk_mul_f32 v[94:95], v[50:51], v[94:95]
	v_pk_mul_f32 v[96:97], v[52:53], v[96:97]
	v_cvt_pk_bf16_f32 v98, v94, v95
	v_cvt_pk_bf16_f32 v99, v96, v97
	global_store_dwordx2 v83, v[98:99], s[6:7] offset:32
; DI unsigned pk_bf16(float lo, float hi) { f32x2 v = {lo, hi}; bf16v2 b = __builtin_convertvector(v, bf16v2); return __builtin_bit_cast(unsigned, b); }
;   DI void operator()(const f32x4 (&acc)[4][4], int r0, int c0, int fr, int fq) const {
;     const int cb = (c0 >> 6) * 32;
; #pragma unroll
;     for (int m = 0; m < 4; ++m)
; #pragma unroll
;       for (int n = 0; n < 2; ++n) {
;         float o[4];
; #pragma unroll
;         for (int j = 0; j < 4; ++j) { float g = acc[m][n][j]; o[j] = g * __builtin_amdgcn_rcpf(1.f + __expf(-g)) * acc[m][n + 2][j]; }
;         u32x2 w = {pk_bf16(o[0], o[1]), pk_bf16(o[2], o[3])};
;         *(u32x2*)(ACT + (size_t)(r0 + m * 16 + fr) * 2816 + cb + n * 16 + fq * 4) = w;
;       }
	v_add_u32_e32 v85, 16, v85
	v_mad_u32_u24 v83, v85, s20, v84
	v_mul_f32_e32 v94, 0xbfb8aa3b, v46
	v_mul_f32_e32 v95, 0xbfb8aa3b, v47
	v_mul_f32_e32 v96, 0xbfb8aa3b, v48
	v_mul_f32_e32 v97, 0xbfb8aa3b, v49
	v_exp_f32_e32 v94, v94
	v_exp_f32_e32 v95, v95
	v_exp_f32_e32 v96, v96
	v_exp_f32_e32 v97, v97
	s_nop 0
	v_add_f32_e32 v94, 1.0, v94
	v_add_f32_e32 v95, 1.0, v95
	v_add_f32_e32 v96, 1.0, v96
	v_add_f32_e32 v97, 1.0, v97
	v_rcp_f32_e32 v94, v94
	v_rcp_f32_e32 v95, v95
	v_rcp_f32_e32 v96, v96
	v_rcp_f32_e32 v97, v97
	s_nop 0
	v_pk_mul_f32 v[94:95], v[46:47], v[94:95]
	v_pk_mul_f32 v[96:97], v[48:49], v[96:97]
	v_pk_mul_f32 v[94:95], v[38:39], v[94:95]
	v_pk_mul_f32 v[96:97], v[40:41], v[96:97]
	v_cvt_pk_bf16_f32 v98, v94, v95
	v_cvt_pk_bf16_f32 v99, v96, v97
	global_store_dwordx2 v83, v[98:99], s[6:7]
	v_mul_f32_e32 v94, 0xbfb8aa3b, v42
	v_mul_f32_e32 v95, 0xbfb8aa3b, v43
	v_mul_f32_e32 v96, 0xbfb8aa3b, v44
	v_mul_f32_e32 v97, 0xbfb8aa3b, v45
	v_exp_f32_e32 v94, v94
	v_exp_f32_e32 v95, v95
	v_exp_f32_e32 v96, v96
	v_exp_f32_e32 v97, v97
	s_nop 0
	v_add_f32_e32 v94, 1.0, v94
	v_add_f32_e32 v95, 1.0, v95
	v_add_f32_e32 v96, 1.0, v96
	v_add_f32_e32 v97, 1.0, v97
	v_rcp_f32_e32 v94, v94
	v_rcp_f32_e32 v95, v95
	v_rcp_f32_e32 v96, v96
	v_rcp_f32_e32 v97, v97
	s_nop 0
	v_pk_mul_f32 v[94:95], v[42:43], v[94:95]
	v_pk_mul_f32 v[96:97], v[44:45], v[96:97]
	v_pk_mul_f32 v[94:95], v[34:35], v[94:95]
	v_pk_mul_f32 v[96:97], v[36:37], v[96:97]
	v_cvt_pk_bf16_f32 v98, v94, v95
	v_cvt_pk_bf16_f32 v99, v96, v97
	global_store_dwordx2 v83, v[98:99], s[6:7] offset:32
	v_add_u32_e32 v85, 16, v85
	v_mad_u32_u24 v83, v85, s20, v84
	v_mul_f32_e32 v94, 0xbfb8aa3b, v30
	v_mul_f32_e32 v95, 0xbfb8aa3b, v31
	v_mul_f32_e32 v96, 0xbfb8aa3b, v32
	v_mul_f32_e32 v97, 0xbfb8aa3b, v33
	v_exp_f32_e32 v94, v94
	v_exp_f32_e32 v95, v95
	v_exp_f32_e32 v96, v96
	v_exp_f32_e32 v97, v97
	s_nop 0
	v_add_f32_e32 v94, 1.0, v94
	v_add_f32_e32 v95, 1.0, v95
	v_add_f32_e32 v96, 1.0, v96
	v_add_f32_e32 v97, 1.0, v97
	v_rcp_f32_e32 v94, v94
	v_rcp_f32_e32 v95, v95
	v_rcp_f32_e32 v96, v96
	v_rcp_f32_e32 v97, v97
	s_nop 0
	v_pk_mul_f32 v[94:95], v[30:31], v[94:95]
	v_pk_mul_f32 v[96:97], v[32:33], v[96:97]
	v_pk_mul_f32 v[94:95], v[22:23], v[94:95]
	v_pk_mul_f32 v[96:97], v[24:25], v[96:97]
	v_cvt_pk_bf16_f32 v98, v94, v95
	v_cvt_pk_bf16_f32 v99, v96, v97
	global_store_dwordx2 v83, v[98:99], s[6:7]
	v_mul_f32_e32 v94, 0xbfb8aa3b, v26
	v_mul_f32_e32 v95, 0xbfb8aa3b, v27
	v_mul_f32_e32 v96, 0xbfb8aa3b, v28
	v_mul_f32_e32 v97, 0xbfb8aa3b, v29
	v_exp_f32_e32 v94, v94
	v_exp_f32_e32 v95, v95
	v_exp_f32_e32 v96, v96
	v_exp_f32_e32 v97, v97
	s_nop 0
	v_add_f32_e32 v94, 1.0, v94
	v_add_f32_e32 v95, 1.0, v95
	v_add_f32_e32 v96, 1.0, v96
	v_add_f32_e32 v97, 1.0, v97
	v_rcp_f32_e32 v94, v94
	v_rcp_f32_e32 v95, v95
	v_rcp_f32_e32 v96, v96
	v_rcp_f32_e32 v97, v97
	s_nop 0
	v_pk_mul_f32 v[94:95], v[26:27], v[94:95]
	v_pk_mul_f32 v[96:97], v[28:29], v[96:97]
	v_pk_mul_f32 v[94:95], v[18:19], v[94:95]
	v_pk_mul_f32 v[96:97], v[20:21], v[96:97]
	v_cvt_pk_bf16_f32 v98, v94, v95
	v_cvt_pk_bf16_f32 v99, v96, v97
	global_store_dwordx2 v83, v[98:99], s[6:7] offset:32
	v_add_u32_e32 v85, 16, v85
	v_mad_u32_u24 v83, v85, s20, v84
	v_mul_f32_e32 v94, 0xbfb8aa3b, v14
	v_mul_f32_e32 v95, 0xbfb8aa3b, v15
	v_mul_f32_e32 v96, 0xbfb8aa3b, v16
	v_mul_f32_e32 v97, 0xbfb8aa3b, v17
	v_exp_f32_e32 v94, v94
	v_exp_f32_e32 v95, v95
	v_exp_f32_e32 v96, v96
	v_exp_f32_e32 v97, v97
	s_nop 0
	v_add_f32_e32 v94, 1.0, v94
	v_add_f32_e32 v95, 1.0, v95
	v_add_f32_e32 v96, 1.0, v96
	v_add_f32_e32 v97, 1.0, v97
	v_rcp_f32_e32 v94, v94
	v_rcp_f32_e32 v95, v95
	v_rcp_f32_e32 v96, v96
	v_rcp_f32_e32 v97, v97
	s_nop 0
	v_pk_mul_f32 v[94:95], v[14:15], v[94:95]
	v_pk_mul_f32 v[96:97], v[16:17], v[96:97]
	v_pk_mul_f32 v[94:95], v[6:7], v[94:95]
	v_pk_mul_f32 v[96:97], v[8:9], v[96:97]
	v_cvt_pk_bf16_f32 v98, v94, v95
	v_cvt_pk_bf16_f32 v99, v96, v97
	global_store_dwordx2 v83, v[98:99], s[6:7]
	v_mul_f32_e32 v94, 0xbfb8aa3b, v10
	v_mul_f32_e32 v95, 0xbfb8aa3b, v11
	v_mul_f32_e32 v96, 0xbfb8aa3b, v12
	v_mul_f32_e32 v97, 0xbfb8aa3b, v13
	v_exp_f32_e32 v94, v94
	v_exp_f32_e32 v95, v95
	v_exp_f32_e32 v96, v96
	v_exp_f32_e32 v97, v97
	s_nop 0
	v_add_f32_e32 v94, 1.0, v94
	v_add_f32_e32 v95, 1.0, v95
	v_add_f32_e32 v96, 1.0, v96
	v_add_f32_e32 v97, 1.0, v97
	v_rcp_f32_e32 v94, v94
	v_rcp_f32_e32 v95, v95
	v_rcp_f32_e32 v96, v96
	v_rcp_f32_e32 v97, v97
	s_nop 0
	v_pk_mul_f32 v[94:95], v[10:11], v[94:95]
	v_pk_mul_f32 v[96:97], v[12:13], v[96:97]
	v_pk_mul_f32 v[94:95], v[2:3], v[94:95]
	v_pk_mul_f32 v[96:97], v[4:5], v[96:97]
	v_cvt_pk_bf16_f32 v98, v94, v95
	v_cvt_pk_bf16_f32 v99, v96, v97
	global_store_dwordx2 v83, v[98:99], s[6:7] offset:32
	v_mov_b32_e32 v2, v162
	v_mov_b32_e32 v3, v163
	v_mov_b32_e32 v4, v164
	v_mov_b32_e32 v5, v165
	v_mov_b32_e32 v6, v166
	v_mov_b32_e32 v7, v167
	v_mov_b32_e32 v8, v168
	v_mov_b32_e32 v9, v169
	v_mov_b32_e32 v10, v170
	v_mov_b32_e32 v11, v171
	v_mov_b32_e32 v12, v172
	v_mov_b32_e32 v13, v173
	v_mov_b32_e32 v14, v174
	v_mov_b32_e32 v15, v175
	v_mov_b32_e32 v16, v176
	v_mov_b32_e32 v17, v177
	v_mov_b32_e32 v18, v178
	v_mov_b32_e32 v19, v179
	v_mov_b32_e32 v20, v180
	v_mov_b32_e32 v21, v181
	v_mov_b32_e32 v22, v182
	v_mov_b32_e32 v23, v183
	v_mov_b32_e32 v24, v184
	v_mov_b32_e32 v25, v185
	v_mov_b32_e32 v26, v186
	v_mov_b32_e32 v27, v187
	v_mov_b32_e32 v28, v188
	v_mov_b32_e32 v29, v189
	v_mov_b32_e32 v30, v190
	v_mov_b32_e32 v31, v191
	v_mov_b32_e32 v32, v192
	v_mov_b32_e32 v33, v193
	v_mov_b32_e32 v34, v194
	v_mov_b32_e32 v35, v195
	v_mov_b32_e32 v36, v196
	v_mov_b32_e32 v37, v197
	v_mov_b32_e32 v38, v198
; DI unsigned pk_bf16(float lo, float hi) { f32x2 v = {lo, hi}; bf16v2 b = __builtin_convertvector(v, bf16v2); return __builtin_bit_cast(unsigned, b); }
;   DI void operator()(const f32x4 (&acc)[4][4], int r0, int c0, int fr, int fq) const {
;     const int cb = (c0 >> 6) * 32;
; #pragma unroll
;     for (int m = 0; m < 4; ++m)
; #pragma unroll
;       for (int n = 0; n < 2; ++n) {
;         float o[4];
; #pragma unroll
;         for (int j = 0; j < 4; ++j) { float g = acc[m][n][j]; o[j] = g * __builtin_amdgcn_rcpf(1.f + __expf(-g)) * acc[m][n + 2][j]; }
;         u32x2 w = {pk_bf16(o[0], o[1]), pk_bf16(o[2], o[3])};
;         *(u32x2*)(ACT + (size_t)(r0 + m * 16 + fr) * 2816 + cb + n * 16 + fq * 4) = w;
;       }
	v_mov_b32_e32 v39, v199
	v_mov_b32_e32 v40, v200
	v_mov_b32_e32 v41, v201
	v_mov_b32_e32 v42, v202
	v_mov_b32_e32 v43, v203
	v_mov_b32_e32 v44, v204
	v_mov_b32_e32 v45, v205
	v_mov_b32_e32 v46, v206
	v_mov_b32_e32 v47, v207
	v_mov_b32_e32 v48, v208
	v_mov_b32_e32 v49, v209
	v_mov_b32_e32 v50, v210
	v_mov_b32_e32 v51, v211
	v_mov_b32_e32 v52, v212
	v_mov_b32_e32 v53, v213
	v_mov_b32_e32 v54, v214
	v_mov_b32_e32 v55, v215
	v_mov_b32_e32 v56, v216
	v_mov_b32_e32 v57, v217
	v_mov_b32_e32 v58, v218
	v_mov_b32_e32 v59, v219
	v_mov_b32_e32 v60, v220
	v_mov_b32_e32 v61, v221
	v_mov_b32_e32 v62, v222
	v_mov_b32_e32 v63, v223
	v_mov_b32_e32 v64, v224
	v_mov_b32_e32 v65, v225
	s_add_i32 s21, s2, 0x80
	v_or_b32_e32 v85, s21, v87
	v_lshl_add_u32 v85, v88, 6, v85
	v_mad_u32_u24 v83, v85, s20, v84
	v_mul_f32_e32 v94, 0xbfb8aa3b, v62
	v_mul_f32_e32 v95, 0xbfb8aa3b, v63
	v_mul_f32_e32 v96, 0xbfb8aa3b, v64
	v_mul_f32_e32 v97, 0xbfb8aa3b, v65
	v_exp_f32_e32 v94, v94
	v_exp_f32_e32 v95, v95
	v_exp_f32_e32 v96, v96
	v_exp_f32_e32 v97, v97
	s_nop 0
	v_add_f32_e32 v94, 1.0, v94
	v_add_f32_e32 v95, 1.0, v95
	v_add_f32_e32 v96, 1.0, v96
	v_add_f32_e32 v97, 1.0, v97
	v_rcp_f32_e32 v94, v94
	v_rcp_f32_e32 v95, v95
	v_rcp_f32_e32 v96, v96
	v_rcp_f32_e32 v97, v97
	s_nop 0
	v_pk_mul_f32 v[94:95], v[62:63], v[94:95]
	v_pk_mul_f32 v[96:97], v[64:65], v[96:97]
	v_pk_mul_f32 v[94:95], v[54:55], v[94:95]
	v_pk_mul_f32 v[96:97], v[56:57], v[96:97]
	v_cvt_pk_bf16_f32 v98, v94, v95
	v_cvt_pk_bf16_f32 v99, v96, v97
	global_store_dwordx2 v83, v[98:99], s[6:7]
	v_mul_f32_e32 v94, 0xbfb8aa3b, v58
	v_mul_f32_e32 v95, 0xbfb8aa3b, v59
	v_mul_f32_e32 v96, 0xbfb8aa3b, v60
	v_mul_f32_e32 v97, 0xbfb8aa3b, v61
	v_exp_f32_e32 v94, v94
	v_exp_f32_e32 v95, v95
	v_exp_f32_e32 v96, v96
	v_exp_f32_e32 v97, v97
	s_nop 0
	v_add_f32_e32 v94, 1.0, v94
	v_add_f32_e32 v95, 1.0, v95
	v_add_f32_e32 v96, 1.0, v96
	v_add_f32_e32 v97, 1.0, v97
	v_rcp_f32_e32 v94, v94
	v_rcp_f32_e32 v95, v95
	v_rcp_f32_e32 v96, v96
	v_rcp_f32_e32 v97, v97
	s_nop 0
	v_pk_mul_f32 v[94:95], v[58:59], v[94:95]
	v_pk_mul_f32 v[96:97], v[60:61], v[96:97]
	v_pk_mul_f32 v[94:95], v[50:51], v[94:95]
	v_pk_mul_f32 v[96:97], v[52:53], v[96:97]
	v_cvt_pk_bf16_f32 v98, v94, v95
	v_cvt_pk_bf16_f32 v99, v96, v97
	global_store_dwordx2 v83, v[98:99], s[6:7] offset:32
	v_add_u32_e32 v85, 16, v85
	v_mad_u32_u24 v83, v85, s20, v84
	v_mul_f32_e32 v94, 0xbfb8aa3b, v46
	v_mul_f32_e32 v95, 0xbfb8aa3b, v47
	v_mul_f32_e32 v96, 0xbfb8aa3b, v48
	v_mul_f32_e32 v97, 0xbfb8aa3b, v49
	v_exp_f32_e32 v94, v94
	v_exp_f32_e32 v95, v95
	v_exp_f32_e32 v96, v96
	v_exp_f32_e32 v97, v97
	s_nop 0
	v_add_f32_e32 v94, 1.0, v94
	v_add_f32_e32 v95, 1.0, v95
	v_add_f32_e32 v96, 1.0, v96
	v_add_f32_e32 v97, 1.0, v97
	v_rcp_f32_e32 v94, v94
	v_rcp_f32_e32 v95, v95
	v_rcp_f32_e32 v96, v96
	v_rcp_f32_e32 v97, v97
	s_nop 0
	v_pk_mul_f32 v[94:95], v[46:47], v[94:95]
	v_pk_mul_f32 v[96:97], v[48:49], v[96:97]
	v_pk_mul_f32 v[94:95], v[38:39], v[94:95]
	v_pk_mul_f32 v[96:97], v[40:41], v[96:97]
	v_cvt_pk_bf16_f32 v98, v94, v95
	v_cvt_pk_bf16_f32 v99, v96, v97
	global_store_dwordx2 v83, v[98:99], s[6:7]
	v_mul_f32_e32 v94, 0xbfb8aa3b, v42
	v_mul_f32_e32 v95, 0xbfb8aa3b, v43
	v_mul_f32_e32 v96, 0xbfb8aa3b, v44
	v_mul_f32_e32 v97, 0xbfb8aa3b, v45
	v_exp_f32_e32 v94, v94
	v_exp_f32_e32 v95, v95
	v_exp_f32_e32 v96, v96
	v_exp_f32_e32 v97, v97
	s_nop 0
	v_add_f32_e32 v94, 1.0, v94
	v_add_f32_e32 v95, 1.0, v95
	v_add_f32_e32 v96, 1.0, v96
	v_add_f32_e32 v97, 1.0, v97
	v_rcp_f32_e32 v94, v94
	v_rcp_f32_e32 v95, v95
; DI unsigned pk_bf16(float lo, float hi) { f32x2 v = {lo, hi}; bf16v2 b = __builtin_convertvector(v, bf16v2); return __builtin_bit_cast(unsigned, b); }
; DI int lat_tile(int i) { return (i >> 4) * 18 + 2 + (i & 15); }
;   DI void operator()(const f32x4 (&acc)[4][4], int r0, int c0, int fr, int fq) const {
;     const int cb = (c0 >> 6) * 32;
; #pragma unroll
;     for (int m = 0; m < 4; ++m)
; #pragma unroll
;       for (int n = 0; n < 2; ++n) {
;         float o[4];
; #pragma unroll
;         for (int j = 0; j < 4; ++j) { float g = acc[m][n][j]; o[j] = g * __builtin_amdgcn_rcpf(1.f + __expf(-g)) * acc[m][n + 2][j]; }
;         u32x2 w = {pk_bf16(o[0], o[1]), pk_bf16(o[2], o[3])};
;         *(u32x2*)(ACT + (size_t)(r0 + m * 16 + fr) * 2816 + cb + n * 16 + fq * 4) = w;
;       }
; template <int KSEL> DI void run_phase(const Params& p, int ph, char* lds) {
;     ...
;       for (int i = 0, tm, tn; xcd_tile(bid, G, i, nm, 44, tm, tn); ++i) gemm_tile(p.HY, DM, p.Wffi, DM, DM, (last ? lat_tile(tm) : tm) * 128, tn * 128, lds, e);
	v_rcp_f32_e32 v96, v96
	v_rcp_f32_e32 v97, v97
	s_nop 0
	v_pk_mul_f32 v[94:95], v[42:43], v[94:95]
	v_pk_mul_f32 v[96:97], v[44:45], v[96:97]
	v_pk_mul_f32 v[94:95], v[34:35], v[94:95]
	v_pk_mul_f32 v[96:97], v[36:37], v[96:97]
	v_cvt_pk_bf16_f32 v98, v94, v95
	v_cvt_pk_bf16_f32 v99, v96, v97
	global_store_dwordx2 v83, v[98:99], s[6:7] offset:32
	v_add_u32_e32 v85, 16, v85
	v_mad_u32_u24 v83, v85, s20, v84
	v_mul_f32_e32 v94, 0xbfb8aa3b, v30
	v_mul_f32_e32 v95, 0xbfb8aa3b, v31
	v_mul_f32_e32 v96, 0xbfb8aa3b, v32
	v_mul_f32_e32 v97, 0xbfb8aa3b, v33
	v_exp_f32_e32 v94, v94
	v_exp_f32_e32 v95, v95
	v_exp_f32_e32 v96, v96
	v_exp_f32_e32 v97, v97
	s_nop 0
	v_add_f32_e32 v94, 1.0, v94
	v_add_f32_e32 v95, 1.0, v95
	v_add_f32_e32 v96, 1.0, v96
	v_add_f32_e32 v97, 1.0, v97
	v_rcp_f32_e32 v94, v94
	v_rcp_f32_e32 v95, v95
	v_rcp_f32_e32 v96, v96
	v_rcp_f32_e32 v97, v97
	s_nop 0
	v_pk_mul_f32 v[94:95], v[30:31], v[94:95]
	v_pk_mul_f32 v[96:97], v[32:33], v[96:97]
	v_pk_mul_f32 v[94:95], v[22:23], v[94:95]
	v_pk_mul_f32 v[96:97], v[24:25], v[96:97]
	v_cvt_pk_bf16_f32 v98, v94, v95
	v_cvt_pk_bf16_f32 v99, v96, v97
	global_store_dwordx2 v83, v[98:99], s[6:7]
	v_mul_f32_e32 v94, 0xbfb8aa3b, v26
	v_mul_f32_e32 v95, 0xbfb8aa3b, v27
	v_mul_f32_e32 v96, 0xbfb8aa3b, v28
	v_mul_f32_e32 v97, 0xbfb8aa3b, v29
	v_exp_f32_e32 v94, v94
	v_exp_f32_e32 v95, v95
	v_exp_f32_e32 v96, v96
	v_exp_f32_e32 v97, v97
	s_nop 0
	v_add_f32_e32 v94, 1.0, v94
	v_add_f32_e32 v95, 1.0, v95
	v_add_f32_e32 v96, 1.0, v96
	v_add_f32_e32 v97, 1.0, v97
	v_rcp_f32_e32 v94, v94
	v_rcp_f32_e32 v95, v95
	v_rcp_f32_e32 v96, v96
	v_rcp_f32_e32 v97, v97
	s_nop 0
	v_pk_mul_f32 v[94:95], v[26:27], v[94:95]
	v_pk_mul_f32 v[96:97], v[28:29], v[96:97]
	v_pk_mul_f32 v[94:95], v[18:19], v[94:95]
	v_pk_mul_f32 v[96:97], v[20:21], v[96:97]
	v_cvt_pk_bf16_f32 v98, v94, v95
	v_cvt_pk_bf16_f32 v99, v96, v97
	global_store_dwordx2 v83, v[98:99], s[6:7] offset:32
	v_add_u32_e32 v85, 16, v85
	v_mad_u32_u24 v83, v85, s20, v84
	v_mul_f32_e32 v94, 0xbfb8aa3b, v14
	v_mul_f32_e32 v95, 0xbfb8aa3b, v15
	v_mul_f32_e32 v96, 0xbfb8aa3b, v16
	v_mul_f32_e32 v97, 0xbfb8aa3b, v17
	v_exp_f32_e32 v94, v94
	v_exp_f32_e32 v95, v95
	v_exp_f32_e32 v96, v96
	v_exp_f32_e32 v97, v97
	s_nop 0
	v_add_f32_e32 v94, 1.0, v94
	v_add_f32_e32 v95, 1.0, v95
	v_add_f32_e32 v96, 1.0, v96
	v_add_f32_e32 v97, 1.0, v97
	v_rcp_f32_e32 v94, v94
	v_rcp_f32_e32 v95, v95
	v_rcp_f32_e32 v96, v96
	v_rcp_f32_e32 v97, v97
	s_nop 0
	v_pk_mul_f32 v[94:95], v[14:15], v[94:95]
	v_pk_mul_f32 v[96:97], v[16:17], v[96:97]
	v_pk_mul_f32 v[94:95], v[6:7], v[94:95]
	v_pk_mul_f32 v[96:97], v[8:9], v[96:97]
	v_cvt_pk_bf16_f32 v98, v94, v95
	v_cvt_pk_bf16_f32 v99, v96, v97
	global_store_dwordx2 v83, v[98:99], s[6:7]
	v_mul_f32_e32 v94, 0xbfb8aa3b, v10
	v_mul_f32_e32 v95, 0xbfb8aa3b, v11
	v_mul_f32_e32 v96, 0xbfb8aa3b, v12
	v_mul_f32_e32 v97, 0xbfb8aa3b, v13
	v_exp_f32_e32 v94, v94
	v_exp_f32_e32 v95, v95
	v_exp_f32_e32 v96, v96
	v_exp_f32_e32 v97, v97
	s_nop 0
	v_add_f32_e32 v94, 1.0, v94
	v_add_f32_e32 v95, 1.0, v95
	v_add_f32_e32 v96, 1.0, v96
	v_add_f32_e32 v97, 1.0, v97
	v_rcp_f32_e32 v94, v94
	v_rcp_f32_e32 v95, v95
	v_rcp_f32_e32 v96, v96
	v_rcp_f32_e32 v97, v97
	s_nop 0
	v_pk_mul_f32 v[94:95], v[10:11], v[94:95]
	v_pk_mul_f32 v[96:97], v[12:13], v[96:97]
	v_pk_mul_f32 v[94:95], v[2:3], v[94:95]
	v_pk_mul_f32 v[96:97], v[4:5], v[96:97]
	v_cvt_pk_bf16_f32 v98, v94, v95
	v_cvt_pk_bf16_f32 v99, v96, v97
	global_store_dwordx2 v83, v[98:99], s[6:7] offset:32
	s_mov_b64 s[2:3], 0
	s_branch .LBB0_120
